# uk epilogue: hoist the 8 rowsum loads ahead of the first group, remove per-group load/store-drain waits
# speedup vs baseline: 1.0124x; 1.0001x over previous
; #define GLDS16(gp, lp) __builtin_amdgcn_global_load_lds((const unsigned*)(gp), (__attribute__((address_space(3))) unsigned*)(lp), 16, 0, 0)
; template <bool SWAP, class Epi, bool THIN = false> ...
;     ...
;   for (; v < voff + ntiles; v += grid) {
;     const int w = v - voff;
;     int mt, nt;
;     if (w < full * 8 * NT) { const int sr = w / (8 * NT), rem = w - sr * 8 * NT; nt = rem >> 3; mt = sr * 8 + (rem & 7); }
;     else { const int w2 = w - full * 8 * NT, rl = MT - full * 8; nt = w2 / rl; mt = full * 8 + (w2 - nt * rl); }
;     unsigned ap[4], bp[4];
; #pragma unroll
;     for (int i = 0; i < 4; ++i) {
;       const int r = (tid >> 3) + 64 * i;
;       const int cs = tid & 7;
;       const int c = ((cs ^ ((r >> 1) & 7)) << 3);
;       const int sub = 2 * mt + (r >> 7);
;       const int g = sub / tpg, ti = sub - g * tpg;
;       int rig = ti * step - halo + (r & 127); rig = rig < 0 ? 0 : (rig > grows - 1 ? grows - 1 : rig);
;       ap[i] = (unsigned)((g * a_gstride + a_goff + rig) * lda + c);
;       int br = nt * 256 + r; br = br > N - 1 ? N - 1 : br;
;       bp[i] = (unsigned)(br * K + c);
;     }
;     const bool have_next = false;
;     f32x4 acc[4][8];
; #pragma unroll
;     for (int m = 0; m < 4; ++m)
; #pragma unroll
;       for (int n = 0; n < 8; ++n) acc[m][n] = (f32x4){0.f, 0.f, 0.f, 0.f};
;     if (!pre_issued) {
; #pragma unroll
;       for (int i = 0; i < 4; ++i) { GLDS16(A + (size_t)ap[i], smem + tid * 16 + i * 8192); GLDS16(Bt + (size_t)bp[i], smem + 32768 + tid * 16 + i * 8192); }
;     }
;     pre_issued = have_next;
;     for (int st = 0; st < ns; ++st) {
;       asm volatile("s_waitcnt vmcnt(0)" ::: "memory");
;       __builtin_amdgcn_s_barrier();
;       asm volatile("" ::: "memory");
;       if (st + 1 < ns) {
;         char* nb = smem + ((st + 1) & 1) * 65536;
;         const int ko = (st + 1) * 64;
; #pragma unroll
;         for (int i = 0; i < 4; ++i) { GLDS16(A + (size_t)(ap[i] + ko), nb + tid * 16 + i * 8192); GLDS16(Bt + (size_t)(bp[i] + ko), nb + 32768 + tid * 16 + i * 8192); }
;       }
.LBB0_1818:
	s_add_i32 s4, s33, 0xfffffe80
	s_ashr_i32 s5, s4, 31
	s_lshr_b32 s5, s5, 27
	s_add_i32 s4, s4, s5
	s_ashr_i32 s4, s4, 5
	s_lshl_b32 s5, s4, 4
	s_and_b32 s6, s38, 14
	s_or_b32 s5, s5, s6
	v_add_u32_e32 v2, s5, v139
	v_mul_hi_i32 v3, v2, s42
	v_lshrrev_b32_e32 v4, 31, v3
	v_ashrrev_i32_e32 v3, 2, v3
	v_add_u32_e32 v4, v3, v4
	v_mad_u64_u32 v[2:3], s[6:7], v4, s43, v[2:3]
	v_lshl_or_b32 v3, v2, 7, v140
	v_min_i32_e32 v3, 0x8ff, v3
	v_cmp_lt_i32_e32 vcc, -1, v2
	s_lshl_b32 s4, s4, 10
	s_sub_i32 s4, s40, s4
	v_cndmask_b32_e32 v2, 0, v3, vcc
	v_mad_u64_u32 v[2:3], s[6:7], v4, s44, v[2:3]
	s_and_b32 s4, s4, 0xffffff00
	v_mad_u64_u32 v[2:3], s[6:7], v2, s45, v[130:131]
	v_add_u32_e32 v3, s4, v131
	v_min_i32_e32 v3, 0x3ff, v3
	v_add_u32_e32 v4, s5, v142
	v_lshl_or_b32 v132, v3, 8, v130
	v_mul_hi_i32 v3, v4, s42
	v_lshrrev_b32_e32 v5, 31, v3
	v_ashrrev_i32_e32 v3, 2, v3
	v_add_u32_e32 v3, v3, v5
	v_mad_u64_u32 v[4:5], s[6:7], v3, s43, v[4:5]
	v_lshl_or_b32 v5, v4, 7, v143
	v_min_i32_e32 v5, 0x8ff, v5
	v_cmp_lt_i32_e32 vcc, -1, v4
	v_add_u32_e32 v6, s5, v145
	v_add_u32_e32 v8, s5, v147
	v_cndmask_b32_e32 v4, 0, v5, vcc
	v_mad_u64_u32 v[4:5], s[6:7], v3, s44, v[4:5]
	v_add_u32_e32 v3, s4, v141
	v_min_i32_e32 v3, 0x3ff, v3
	v_mad_u64_u32 v[4:5], s[6:7], v4, s45, v[130:131]
	v_lshl_or_b32 v12, v3, 8, v130
	v_mul_hi_i32 v3, v6, s42
	v_lshrrev_b32_e32 v5, 31, v3
	v_ashrrev_i32_e32 v3, 2, v3
	v_add_u32_e32 v3, v3, v5
	v_mad_u64_u32 v[6:7], s[6:7], v3, s43, v[6:7]
	v_lshl_or_b32 v5, v6, 7, v140
	v_min_i32_e32 v5, 0x8ff, v5
	v_cmp_lt_i32_e32 vcc, -1, v6
	v_readfirstlane_b32 s37, v138
	s_mov_b32 m0, s37
	v_cndmask_b32_e32 v6, 0, v5, vcc
	v_mad_u64_u32 v[6:7], s[6:7], v3, s44, v[6:7]
	v_add_u32_e32 v3, s4, v144
	v_min_i32_e32 v3, 0x3ff, v3
	v_lshl_or_b32 v14, v3, 8, v130
	v_mul_hi_i32 v3, v8, s42
	v_lshrrev_b32_e32 v5, 31, v3
	v_ashrrev_i32_e32 v3, 2, v3
	v_add_u32_e32 v3, v3, v5
	v_mad_u64_u32 v[8:9], s[6:7], v3, s43, v[8:9]
	v_lshl_or_b32 v5, v8, 7, v148
	v_min_i32_e32 v5, 0x8ff, v5
	v_cmp_lt_i32_e32 vcc, -1, v8
	v_readfirstlane_b32 s15, v149
	v_readfirstlane_b32 s14, v150
	v_cndmask_b32_e32 v8, 0, v5, vcc
	v_mad_u64_u32 v[8:9], s[6:7], v3, s44, v[8:9]
	v_add_u32_e32 v3, s4, v146
	v_min_i32_e32 v3, 0x3ff, v3
	v_lshl_or_b32 v16, v3, 8, v130
	v_mov_b32_e32 v3, v133
	v_lshl_add_u64 v[10:11], v[2:3], 1, s[28:29]
	global_load_lds_dwordx4 v[10:11], off
	v_lshl_add_u64 v[10:11], v[132:133], 1, s[20:21]
	s_mov_b32 m0, s15
	v_mov_b32_e32 v5, v133
	v_mad_u64_u32 v[6:7], s[6:7], v6, s45, v[130:131]
	global_load_lds_dwordx4 v[10:11], off
	v_lshl_add_u64 v[18:19], v[4:5], 1, s[28:29]
	s_mov_b32 m0, s14
	v_mov_b32_e32 v13, v133
	v_readfirstlane_b32 s17, v151
	global_load_lds_dwordx4 v[18:19], off
	v_lshl_add_u64 v[12:13], v[12:13], 1, s[20:21]
	s_mov_b32 m0, s17
	v_mov_b32_e32 v7, v133
	v_readfirstlane_b32 s16, v152
	v_mad_u64_u32 v[8:9], s[6:7], v8, s45, v[130:131]
	global_load_lds_dwordx4 v[12:13], off
	v_lshl_add_u64 v[18:19], v[6:7], 1, s[28:29]
	s_mov_b32 m0, s16
	v_mov_b32_e32 v15, v133
	v_readfirstlane_b32 s19, v153
	global_load_lds_dwordx4 v[18:19], off
	v_lshl_add_u64 v[14:15], v[14:15], 1, s[20:21]
	s_mov_b32 m0, s19
	v_mov_b32_e32 v9, v133
	v_readfirstlane_b32 s18, v154
	global_load_lds_dwordx4 v[14:15], off
	v_lshl_add_u64 v[18:19], v[8:9], 1, s[28:29]
	s_mov_b32 m0, s18
	v_mov_b32_e32 v17, v133
	v_readfirstlane_b32 s36, v155
	global_load_lds_dwordx4 v[18:19], off
	v_lshl_add_u64 v[16:17], v[16:17], 1, s[20:21]
	s_mov_b32 m0, s36
	v_add_u32_e32 v132, 64, v2
	global_load_lds_dwordx4 v[16:17], off
	v_readfirstlane_b32 s13, v156
	s_waitcnt vmcnt(0)
	s_barrier
	v_lshl_add_u64 v[18:19], v[132:133], 1, s[28:29]
	s_mov_b32 m0, s13
	v_readfirstlane_b32 s8, v157
	global_load_lds_dwordx4 v[18:19], off
	v_lshl_add_u64 v[18:19], v[10:11], 0, s[24:25]
	s_mov_b32 m0, s8
	v_add_u32_e32 v132, 64, v4
	v_readfirstlane_b32 s7, v158
	global_load_lds_dwordx4 v[18:19], off
	v_lshl_add_u64 v[18:19], v[132:133], 1, s[28:29]
	s_mov_b32 m0, s7
	v_readfirstlane_b32 s6, v159
	global_load_lds_dwordx4 v[18:19], off
	v_lshl_add_u64 v[18:19], v[12:13], 0, s[24:25]
	s_mov_b32 m0, s6
	v_add_u32_e32 v132, 64, v6
	v_readfirstlane_b32 s9, v160
	global_load_lds_dwordx4 v[18:19], off
	v_lshl_add_u64 v[18:19], v[132:133], 1, s[28:29]
	s_mov_b32 m0, s9
	v_readfirstlane_b32 s10, v161
	global_load_lds_dwordx4 v[18:19], off
	v_lshl_add_u64 v[18:19], v[14:15], 0, s[24:25]
	s_mov_b32 m0, s10
	v_add_u32_e32 v132, 64, v8
	v_readfirstlane_b32 s11, v162
	global_load_lds_dwordx4 v[18:19], off
	v_lshl_add_u64 v[18:19], v[132:133], 1, s[28:29]
	s_mov_b32 m0, s11
	v_readfirstlane_b32 s12, v163
	global_load_lds_dwordx4 v[18:19], off
	v_lshl_add_u64 v[18:19], v[16:17], 0, s[24:25]
	s_mov_b32 m0, s12
	s_nop 0
	global_load_lds_dwordx4 v[18:19], off
	ds_read_b128 v[18:21], v164
	ds_read_b128 v[22:25], v164 offset:2048
	ds_read_b128 v[26:29], v164 offset:4096
	ds_read_b128 v[30:33], v164 offset:6144
	ds_read_b128 v[34:37], v165 offset:32768
	ds_read_b128 v[38:41], v165 offset:34816
	ds_read_b128 v[42:45], v165 offset:36864
	ds_read_b128 v[46:49], v165 offset:38912
	ds_read_b128 v[74:77], v165 offset:40960
	ds_read_b128 v[78:81], v165 offset:43008
	s_waitcnt lgkmcnt(0)
; template <bool SWAP, class Epi, bool THIN = false> ...
;     ...
;     for (int st = 0; st < ns; ++st) {
;       asm volatile("s_waitcnt vmcnt(0)" ::: "memory");
;       __builtin_amdgcn_s_barrier();
;       asm volatile("" ::: "memory");
;       if (st + 1 < ns) {
;         char* nb = smem + ((st + 1) & 1) * 65536;
;         const int ko = (st + 1) * 64;
; #pragma unroll
;         for (int i = 0; i < 4; ++i) { GLDS16(A + (size_t)(ap[i] + ko), nb + tid * 16 + i * 8192); GLDS16(Bt + (size_t)(bp[i] + ko), nb + 32768 + tid * 16 + i * 8192); }
;       }
;       const char* sa = smem + (st & 1) * 65536 + (wr * 64 + fr) * 128;
;       const char* sb = smem + (st & 1) * 65536 + 32768 + (wc * 128 + fr) * 128;
;       if constexpr (THIN) {
;         if (wc == 0) {
; #pragma unroll
;           for (int ks = 0; ks < 2; ++ks) {
;             bf16x8 af[4], bf[2];
; #pragma unroll
;             for (int m = 0; m < 4; ++m) af[m] = *(const bf16x8*)(sa + m * 2048 + (((ks * 4 + fq) ^ swz) << 4));
; #pragma unroll
;             for (int n = 0; n < 2; ++n) bf[n] = *(const bf16x8*)(sb + n * 2048 + (((ks * 4 + fq) ^ swz) << 4));
; #pragma unroll
;             for (int m = 0; m < 4; ++m)
; #pragma unroll
;               for (int n = 0; n < 2; ++n)
;                 acc[m][n] = SWAP ? __builtin_amdgcn_mfma_f32_16x16x32_bf16(bf[n], af[m], acc[m][n], 0, 0, 0)
;                                  : __builtin_amdgcn_mfma_f32_16x16x32_bf16(af[m], bf[n], acc[m][n], 0, 0, 0);
;           }
;         }
;       } else {
;       bf16x8 afA[4], afB[4], bfb[2][2];
; #pragma unroll
;       for (int m = 0; m < 4; ++m) afA[m] = *(const bf16x8*)(sa + m * 2048 + ((fq ^ swz) << 4));
; #pragma unroll
;       for (int n = 0; n < 2; ++n) bfb[0][n] = *(const bf16x8*)(sb + n * 2048 + ((fq ^ swz) << 4));
; #pragma unroll
;       for (int gq = 0; gq < 8; ++gq) {
;         const int ks = gq >> 2, nh = gq & 3;
;         if (gq < 7) {
;           const int ks2 = (gq + 1) >> 2, nh2 = (gq + 1) & 3;
; #pragma unroll
;           for (int n = 0; n < 2; ++n) bfb[(gq + 1) & 1][n] = *(const bf16x8*)(sb + (nh2 * 2 + n) * 2048 + (((ks2 * 4 + fq) ^ swz) << 4));
;         }
;         if (gq == 3) {
; #pragma unroll
;           for (int m = 0; m < 4; ++m) afB[m] = *(const bf16x8*)(sa + m * 2048 + (((4 + fq) ^ swz) << 4));
;         }
;         __builtin_amdgcn_sched_barrier(0);
; #pragma unroll
	v_mfma_f32_16x16x32_bf16 v[50:53], v[34:37], v[18:21], 0
	v_mfma_f32_16x16x32_bf16 v[54:57], v[38:41], v[18:21], 0
	v_mfma_f32_16x16x32_bf16 v[58:61], v[34:37], v[22:25], 0
	v_mfma_f32_16x16x32_bf16 v[62:65], v[38:41], v[22:25], 0
	v_mfma_f32_16x16x32_bf16 v[66:69], v[34:37], v[26:29], 0
	v_mfma_f32_16x16x32_bf16 v[70:73], v[38:41], v[26:29], 0
	v_mfma_f32_16x16x32_bf16 v[34:37], v[34:37], v[30:33], 0
	v_mfma_f32_16x16x32_bf16 v[38:41], v[38:41], v[30:33], 0
	ds_read_b128 v[106:109], v165 offset:45056
	ds_read_b128 v[110:113], v165 offset:47104
	v_mfma_f32_16x16x32_bf16 v[82:85], v[42:45], v[18:21], 0
	v_mfma_f32_16x16x32_bf16 v[86:89], v[46:49], v[18:21], 0
	v_mfma_f32_16x16x32_bf16 v[90:93], v[42:45], v[22:25], 0
	v_mfma_f32_16x16x32_bf16 v[94:97], v[46:49], v[22:25], 0
	v_mfma_f32_16x16x32_bf16 v[98:101], v[42:45], v[26:29], 0
	v_mfma_f32_16x16x32_bf16 v[102:105], v[46:49], v[26:29], 0
	v_mfma_f32_16x16x32_bf16 v[42:45], v[42:45], v[30:33], 0
	v_mfma_f32_16x16x32_bf16 v[46:49], v[46:49], v[30:33], 0
	ds_read_b128 v[178:181], v166 offset:32768
	ds_read_b128 v[182:185], v166 offset:34816
	ds_read_b128 v[186:189], v167
	ds_read_b128 v[190:193], v167 offset:2048
	ds_read_b128 v[194:197], v167 offset:4096
	ds_read_b128 v[198:201], v167 offset:6144
	v_mfma_f32_16x16x32_bf16 v[114:117], v[74:77], v[18:21], 0
	v_mfma_f32_16x16x32_bf16 v[118:121], v[78:81], v[18:21], 0
	v_mfma_f32_16x16x32_bf16 v[122:125], v[74:77], v[22:25], 0
	v_mfma_f32_16x16x32_bf16 v[126:129], v[78:81], v[22:25], 0
	v_mfma_f32_16x16x32_bf16 v[134:137], v[74:77], v[26:29], 0
	v_mfma_f32_16x16x32_bf16 v[174:177], v[78:81], v[26:29], 0
	v_mfma_f32_16x16x32_bf16 v[74:77], v[74:77], v[30:33], 0
	v_mfma_f32_16x16x32_bf16 v[78:81], v[78:81], v[30:33], 0
	ds_read_b128 v[214:217], v166 offset:36864
	ds_read_b128 v[218:221], v166 offset:38912
	s_waitcnt lgkmcnt(0)
	v_mfma_f32_16x16x32_bf16 v[202:205], v[106:109], v[18:21], 0
	v_mfma_f32_16x16x32_bf16 v[18:21], v[110:113], v[18:21], 0
	v_mfma_f32_16x16x32_bf16 v[206:209], v[106:109], v[22:25], 0
	v_mfma_f32_16x16x32_bf16 v[22:25], v[110:113], v[22:25], 0
	v_mfma_f32_16x16x32_bf16 v[210:213], v[106:109], v[26:29], 0
	v_mfma_f32_16x16x32_bf16 v[26:29], v[110:113], v[26:29], 0
	v_mfma_f32_16x16x32_bf16 v[106:109], v[106:109], v[30:33], 0
	v_mfma_f32_16x16x32_bf16 v[30:33], v[110:113], v[30:33], 0
	v_mfma_f32_16x16x32_bf16 v[50:53], v[178:181], v[186:189], v[50:53]
	v_mfma_f32_16x16x32_bf16 v[58:61], v[178:181], v[190:193], v[58:61]
	v_mfma_f32_16x16x32_bf16 v[66:69], v[178:181], v[194:197], v[66:69]
	v_mfma_f32_16x16x32_bf16 v[34:37], v[178:181], v[198:201], v[34:37]
	ds_read_b128 v[110:113], v166 offset:40960
	ds_read_b128 v[178:181], v166 offset:43008
	v_mfma_f32_16x16x32_bf16 v[54:57], v[182:185], v[186:189], v[54:57]
	v_mfma_f32_16x16x32_bf16 v[62:65], v[182:185], v[190:193], v[62:65]
	v_mfma_f32_16x16x32_bf16 v[70:73], v[182:185], v[194:197], v[70:73]
	v_mfma_f32_16x16x32_bf16 v[38:41], v[182:185], v[198:201], v[38:41]
	v_mfma_f32_16x16x32_bf16 v[82:85], v[214:217], v[186:189], v[82:85]
	v_mfma_f32_16x16x32_bf16 v[90:93], v[214:217], v[190:193], v[90:93]
	v_mfma_f32_16x16x32_bf16 v[98:101], v[214:217], v[194:197], v[98:101]
	v_mfma_f32_16x16x32_bf16 v[42:45], v[214:217], v[198:201], v[42:45]
	ds_read_b128 v[182:185], v166 offset:45056
	ds_read_b128 v[214:217], v166 offset:47104
	v_mfma_f32_16x16x32_bf16 v[86:89], v[218:221], v[186:189], v[86:89]
	v_mfma_f32_16x16x32_bf16 v[94:97], v[218:221], v[190:193], v[94:97]
	v_mfma_f32_16x16x32_bf16 v[102:105], v[218:221], v[194:197], v[102:105]
	v_mfma_f32_16x16x32_bf16 v[46:49], v[218:221], v[198:201], v[46:49]
	s_waitcnt lgkmcnt(0)
	v_mfma_f32_16x16x32_bf16 v[114:117], v[110:113], v[186:189], v[114:117]
	v_mfma_f32_16x16x32_bf16 v[118:121], v[178:181], v[186:189], v[118:121]
	v_mfma_f32_16x16x32_bf16 v[122:125], v[110:113], v[190:193], v[122:125]
	v_mfma_f32_16x16x32_bf16 v[126:129], v[178:181], v[190:193], v[126:129]
	v_mfma_f32_16x16x32_bf16 v[134:137], v[110:113], v[194:197], v[134:137]
	v_mfma_f32_16x16x32_bf16 v[74:77], v[110:113], v[198:201], v[74:77]
	v_mfma_f32_16x16x32_bf16 v[78:81], v[178:181], v[198:201], v[78:81]
	v_mfma_f32_16x16x32_bf16 v[174:177], v[178:181], v[194:197], v[174:177]
	v_add_u32_e32 v132, 0x80, v2
	s_mov_b32 m0, s37
	v_mfma_f32_16x16x32_bf16 v[110:113], v[182:185], v[186:189], v[202:205]
	s_waitcnt vmcnt(0)
	s_barrier
; template <bool SWAP, class Epi, bool THIN = false> ...
;     ...
;     for (int st = 0; st < ns; ++st) {
;       asm volatile("s_waitcnt vmcnt(0)" ::: "memory");
;       __builtin_amdgcn_s_barrier();
;       asm volatile("" ::: "memory");
;       if (st + 1 < ns) {
;         char* nb = smem + ((st + 1) & 1) * 65536;
;         const int ko = (st + 1) * 64;
; #pragma unroll
;         for (int i = 0; i < 4; ++i) { GLDS16(A + (size_t)(ap[i] + ko), nb + tid * 16 + i * 8192); GLDS16(Bt + (size_t)(bp[i] + ko), nb + 32768 + tid * 16 + i * 8192); }
;       }
;       const char* sa = smem + (st & 1) * 65536 + (wr * 64 + fr) * 128;
;       const char* sb = smem + (st & 1) * 65536 + 32768 + (wc * 128 + fr) * 128;
;       if constexpr (THIN) {
;         if (wc == 0) {
; #pragma unroll
;           for (int ks = 0; ks < 2; ++ks) {
;             bf16x8 af[4], bf[2];
; #pragma unroll
;             for (int m = 0; m < 4; ++m) af[m] = *(const bf16x8*)(sa + m * 2048 + (((ks * 4 + fq) ^ swz) << 4));
; #pragma unroll
;             for (int n = 0; n < 2; ++n) bf[n] = *(const bf16x8*)(sb + n * 2048 + (((ks * 4 + fq) ^ swz) << 4));
; #pragma unroll
;             for (int m = 0; m < 4; ++m)
; #pragma unroll
;               for (int n = 0; n < 2; ++n)
;                 acc[m][n] = SWAP ? __builtin_amdgcn_mfma_f32_16x16x32_bf16(bf[n], af[m], acc[m][n], 0, 0, 0)
;                                  : __builtin_amdgcn_mfma_f32_16x16x32_bf16(af[m], bf[n], acc[m][n], 0, 0, 0);
;           }
;         }
;       } else {
;       bf16x8 afA[4], afB[4], bfb[2][2];
; #pragma unroll
;       for (int m = 0; m < 4; ++m) afA[m] = *(const bf16x8*)(sa + m * 2048 + ((fq ^ swz) << 4));
; #pragma unroll
;       for (int n = 0; n < 2; ++n) bfb[0][n] = *(const bf16x8*)(sb + n * 2048 + ((fq ^ swz) << 4));
; #pragma unroll
;       for (int gq = 0; gq < 8; ++gq) {
;         const int ks = gq >> 2, nh = gq & 3;
;         if (gq < 7) {
;           const int ks2 = (gq + 1) >> 2, nh2 = (gq + 1) & 3;
; #pragma unroll
;           for (int n = 0; n < 2; ++n) bfb[(gq + 1) & 1][n] = *(const bf16x8*)(sb + (nh2 * 2 + n) * 2048 + (((ks2 * 4 + fq) ^ swz) << 4));
;         }
;         if (gq == 3) {
; #pragma unroll
;           for (int m = 0; m < 4; ++m) afB[m] = *(const bf16x8*)(sa + m * 2048 + (((4 + fq) ^ swz) << 4));
;         }
;         __builtin_amdgcn_sched_barrier(0);
; #pragma unroll
	v_mfma_f32_16x16x32_bf16 v[18:21], v[214:217], v[186:189], v[18:21]
	v_lshl_add_u64 v[186:187], v[132:133], 1, s[28:29]
	global_load_lds_dwordx4 v[186:187], off
	v_lshl_add_u64 v[186:187], v[10:11], 0, s[30:31]
	s_mov_b32 m0, s15
	v_add_u32_e32 v132, 0x80, v4
	v_mfma_f32_16x16x32_bf16 v[178:181], v[182:185], v[190:193], v[206:209]
	global_load_lds_dwordx4 v[186:187], off
	s_mov_b32 m0, s14
	v_mfma_f32_16x16x32_bf16 v[22:25], v[214:217], v[190:193], v[22:25]
	v_lshl_add_u64 v[190:191], v[132:133], 1, s[28:29]
	global_load_lds_dwordx4 v[190:191], off
	v_lshl_add_u64 v[190:191], v[12:13], 0, s[30:31]
	s_mov_b32 m0, s17
	v_add_u32_e32 v132, 0x80, v6
	global_load_lds_dwordx4 v[190:191], off
	v_lshl_add_u64 v[190:191], v[132:133], 1, s[28:29]
	s_mov_b32 m0, s16
	v_add_u32_e32 v132, 0x80, v8
	global_load_lds_dwordx4 v[190:191], off
	v_lshl_add_u64 v[190:191], v[14:15], 0, s[30:31]
	s_mov_b32 m0, s19
	v_mfma_f32_16x16x32_bf16 v[186:189], v[182:185], v[194:197], v[210:213]
	global_load_lds_dwordx4 v[190:191], off
	v_lshl_add_u64 v[190:191], v[132:133], 1, s[28:29]
	s_mov_b32 m0, s18
	v_mfma_f32_16x16x32_bf16 v[26:29], v[214:217], v[194:197], v[26:29]
	global_load_lds_dwordx4 v[190:191], off
	v_lshl_add_u64 v[190:191], v[16:17], 0, s[30:31]
	s_mov_b32 m0, s36
	v_mfma_f32_16x16x32_bf16 v[106:109], v[182:185], v[198:201], v[106:109]
	global_load_lds_dwordx4 v[190:191], off
	ds_read_b128 v[182:185], v168
	ds_read_b128 v[190:193], v168 offset:2048
	ds_read_b128 v[194:197], v168 offset:4096
	ds_read_b128 v[202:205], v168 offset:6144
	ds_read_b128 v[206:209], v169
	ds_read_b128 v[210:213], v169 offset:2048
	ds_read_b128 v[218:221], v169 offset:4096
	ds_read_b128 v[222:225], v169 offset:6144
	v_mfma_f32_16x16x32_bf16 v[30:33], v[214:217], v[198:201], v[30:33]
	s_waitcnt lgkmcnt(0)
	v_mfma_f32_16x16x32_bf16 v[50:53], v[206:209], v[182:185], v[50:53]
	v_mfma_f32_16x16x32_bf16 v[58:61], v[206:209], v[190:193], v[58:61]
	v_mfma_f32_16x16x32_bf16 v[66:69], v[206:209], v[194:197], v[66:69]
	v_mfma_f32_16x16x32_bf16 v[34:37], v[206:209], v[202:205], v[34:37]
	ds_read_b128 v[198:201], v169 offset:8192
	ds_read_b128 v[206:209], v169 offset:10240
	v_mfma_f32_16x16x32_bf16 v[54:57], v[210:213], v[182:185], v[54:57]
	v_mfma_f32_16x16x32_bf16 v[62:65], v[210:213], v[190:193], v[62:65]
	v_mfma_f32_16x16x32_bf16 v[70:73], v[210:213], v[194:197], v[70:73]
	v_mfma_f32_16x16x32_bf16 v[38:41], v[210:213], v[202:205], v[38:41]
	ds_read_b128 v[210:213], v169 offset:12288
	ds_read_b128 v[214:217], v169 offset:14336
	v_mfma_f32_16x16x32_bf16 v[82:85], v[218:221], v[182:185], v[82:85]
	v_mfma_f32_16x16x32_bf16 v[86:89], v[222:225], v[182:185], v[86:89]
	v_mfma_f32_16x16x32_bf16 v[90:93], v[218:221], v[190:193], v[90:93]
	v_mfma_f32_16x16x32_bf16 v[94:97], v[222:225], v[190:193], v[94:97]
	v_mfma_f32_16x16x32_bf16 v[98:101], v[218:221], v[194:197], v[98:101]
	v_mfma_f32_16x16x32_bf16 v[102:105], v[222:225], v[194:197], v[102:105]
	v_mfma_f32_16x16x32_bf16 v[42:45], v[218:221], v[202:205], v[42:45]
	v_mfma_f32_16x16x32_bf16 v[46:49], v[222:225], v[202:205], v[46:49]
	s_waitcnt lgkmcnt(0)
	v_mfma_f32_16x16x32_bf16 v[114:117], v[198:201], v[182:185], v[114:117]
	ds_read_b128 v[218:221], v170
	ds_read_b128 v[222:225], v170 offset:2048
	v_mfma_f32_16x16x32_bf16 v[122:125], v[198:201], v[190:193], v[122:125]
	v_mfma_f32_16x16x32_bf16 v[134:137], v[198:201], v[194:197], v[134:137]
	v_mfma_f32_16x16x32_bf16 v[74:77], v[198:201], v[202:205], v[74:77]
	ds_read_b128 v[198:201], v171
	ds_read_b128 v[226:229], v171 offset:2048
	ds_read_b128 v[230:233], v171 offset:4096
	ds_read_b128 v[234:237], v171 offset:6144
	v_mfma_f32_16x16x32_bf16 v[118:121], v[206:209], v[182:185], v[118:121]
	v_mfma_f32_16x16x32_bf16 v[126:129], v[206:209], v[190:193], v[126:129]
	v_mfma_f32_16x16x32_bf16 v[78:81], v[206:209], v[202:205], v[78:81]
	v_mfma_f32_16x16x32_bf16 v[174:177], v[206:209], v[194:197], v[174:177]
	v_mfma_f32_16x16x32_bf16 v[110:113], v[210:213], v[182:185], v[110:113]
	v_mfma_f32_16x16x32_bf16 v[18:21], v[214:217], v[182:185], v[18:21]
	v_mfma_f32_16x16x32_bf16 v[178:181], v[210:213], v[190:193], v[178:181]
	v_mfma_f32_16x16x32_bf16 v[22:25], v[214:217], v[190:193], v[22:25]
	v_mfma_f32_16x16x32_bf16 v[182:185], v[210:213], v[194:197], v[186:189]
	s_nop 2
	ds_read_b128 v[186:189], v170 offset:4096
	ds_read_b128 v[190:193], v170 offset:6144
	v_mfma_f32_16x16x32_bf16 v[26:29], v[214:217], v[194:197], v[26:29]
	v_mfma_f32_16x16x32_bf16 v[106:109], v[210:213], v[202:205], v[106:109]
	v_mfma_f32_16x16x32_bf16 v[30:33], v[214:217], v[202:205], v[30:33]
	ds_read_b128 v[194:197], v170 offset:8192
	ds_read_b128 v[202:205], v170 offset:10240
	s_waitcnt lgkmcnt(0)
	v_mfma_f32_16x16x32_bf16 v[50:53], v[218:221], v[198:201], v[50:53]
	v_mfma_f32_16x16x32_bf16 v[54:57], v[222:225], v[198:201], v[54:57]
	v_mfma_f32_16x16x32_bf16 v[58:61], v[218:221], v[226:229], v[58:61]
	v_mfma_f32_16x16x32_bf16 v[62:65], v[222:225], v[226:229], v[62:65]
	v_mfma_f32_16x16x32_bf16 v[66:69], v[218:221], v[230:233], v[66:69]
	v_mfma_f32_16x16x32_bf16 v[70:73], v[222:225], v[230:233], v[70:73]
	v_mfma_f32_16x16x32_bf16 v[34:37], v[218:221], v[234:237], v[34:37]
	v_mfma_f32_16x16x32_bf16 v[38:41], v[222:225], v[234:237], v[38:41]
	v_mfma_f32_16x16x32_bf16 v[82:85], v[186:189], v[198:201], v[82:85]
	v_mfma_f32_16x16x32_bf16 v[90:93], v[186:189], v[226:229], v[90:93]
	v_mfma_f32_16x16x32_bf16 v[98:101], v[186:189], v[230:233], v[98:101]
	v_mfma_f32_16x16x32_bf16 v[42:45], v[186:189], v[234:237], v[42:45]
	ds_read_b128 v[186:189], v170 offset:12288
	ds_read_b128 v[206:209], v170 offset:14336
	v_mfma_f32_16x16x32_bf16 v[86:89], v[190:193], v[198:201], v[86:89]
	v_mfma_f32_16x16x32_bf16 v[94:97], v[190:193], v[226:229], v[94:97]
	v_mfma_f32_16x16x32_bf16 v[102:105], v[190:193], v[230:233], v[102:105]
	v_mfma_f32_16x16x32_bf16 v[46:49], v[190:193], v[234:237], v[46:49]
	v_mfma_f32_16x16x32_bf16 v[114:117], v[194:197], v[198:201], v[114:117]
	v_mfma_f32_16x16x32_bf16 v[118:121], v[202:205], v[198:201], v[118:121]
	v_mfma_f32_16x16x32_bf16 v[122:125], v[194:197], v[226:229], v[122:125]
	v_mfma_f32_16x16x32_bf16 v[126:129], v[202:205], v[226:229], v[126:129]
	v_mfma_f32_16x16x32_bf16 v[134:137], v[194:197], v[230:233], v[134:137]
	v_mfma_f32_16x16x32_bf16 v[74:77], v[194:197], v[234:237], v[74:77]
	v_mfma_f32_16x16x32_bf16 v[78:81], v[202:205], v[234:237], v[78:81]
	v_mfma_f32_16x16x32_bf16 v[174:177], v[202:205], v[230:233], v[174:177]
	v_add_u32_e32 v132, 0xc0, v2
	s_mov_b32 m0, s13
	s_waitcnt vmcnt(0)
	s_barrier
; template <bool SWAP, class Epi, bool THIN = false> ...
;     ...
;     for (int st = 0; st < ns; ++st) {
;       asm volatile("s_waitcnt vmcnt(0)" ::: "memory");
;       __builtin_amdgcn_s_barrier();
;       asm volatile("" ::: "memory");
;       if (st + 1 < ns) {
;         char* nb = smem + ((st + 1) & 1) * 65536;
;         const int ko = (st + 1) * 64;
; #pragma unroll
;         for (int i = 0; i < 4; ++i) { GLDS16(A + (size_t)(ap[i] + ko), nb + tid * 16 + i * 8192); GLDS16(Bt + (size_t)(bp[i] + ko), nb + 32768 + tid * 16 + i * 8192); }
;       }
;       const char* sa = smem + (st & 1) * 65536 + (wr * 64 + fr) * 128;
;       const char* sb = smem + (st & 1) * 65536 + 32768 + (wc * 128 + fr) * 128;
;       if constexpr (THIN) {
;         if (wc == 0) {
; #pragma unroll
;           for (int ks = 0; ks < 2; ++ks) {
;             bf16x8 af[4], bf[2];
; #pragma unroll
;             for (int m = 0; m < 4; ++m) af[m] = *(const bf16x8*)(sa + m * 2048 + (((ks * 4 + fq) ^ swz) << 4));
; #pragma unroll
;             for (int n = 0; n < 2; ++n) bf[n] = *(const bf16x8*)(sb + n * 2048 + (((ks * 4 + fq) ^ swz) << 4));
; #pragma unroll
;             for (int m = 0; m < 4; ++m)
; #pragma unroll
;               for (int n = 0; n < 2; ++n)
;                 acc[m][n] = SWAP ? __builtin_amdgcn_mfma_f32_16x16x32_bf16(bf[n], af[m], acc[m][n], 0, 0, 0)
;                                  : __builtin_amdgcn_mfma_f32_16x16x32_bf16(af[m], bf[n], acc[m][n], 0, 0, 0);
;           }
;         }
;       } else {
;       bf16x8 afA[4], afB[4], bfb[2][2];
; #pragma unroll
;       for (int m = 0; m < 4; ++m) afA[m] = *(const bf16x8*)(sa + m * 2048 + ((fq ^ swz) << 4));
; #pragma unroll
;       for (int n = 0; n < 2; ++n) bfb[0][n] = *(const bf16x8*)(sb + n * 2048 + ((fq ^ swz) << 4));
; #pragma unroll
;       for (int gq = 0; gq < 8; ++gq) {
;         const int ks = gq >> 2, nh = gq & 3;
;         if (gq < 7) {
;           const int ks2 = (gq + 1) >> 2, nh2 = (gq + 1) & 3;
; #pragma unroll
;           for (int n = 0; n < 2; ++n) bfb[(gq + 1) & 1][n] = *(const bf16x8*)(sb + (nh2 * 2 + n) * 2048 + (((ks2 * 4 + fq) ^ swz) << 4));
;         }
;         if (gq == 3) {
; #pragma unroll
;           for (int m = 0; m < 4; ++m) afB[m] = *(const bf16x8*)(sa + m * 2048 + (((4 + fq) ^ swz) << 4));
;         }
;         __builtin_amdgcn_sched_barrier(0);
; #pragma unroll
	v_lshl_add_u64 v[2:3], v[132:133], 1, s[28:29]
	global_load_lds_dwordx4 v[2:3], off
	v_lshl_add_u64 v[2:3], v[10:11], 0, s[34:35]
	s_mov_b32 m0, s8
	v_add_u32_e32 v132, 0xc0, v4
	global_load_lds_dwordx4 v[2:3], off
	v_lshl_add_u64 v[10:11], v[132:133], 1, s[28:29]
	s_mov_b32 m0, s7
	v_add_u32_e32 v132, 0xc0, v6
	global_load_lds_dwordx4 v[10:11], off
	v_lshl_add_u64 v[10:11], v[12:13], 0, s[34:35]
	s_mov_b32 m0, s6
	v_lshl_add_u64 v[6:7], v[132:133], 1, s[28:29]
	global_load_lds_dwordx4 v[10:11], off
	s_mov_b32 m0, s9
	v_add_u32_e32 v132, 0xc0, v8
	global_load_lds_dwordx4 v[6:7], off
	v_lshl_add_u64 v[6:7], v[14:15], 0, s[34:35]
	s_mov_b32 m0, s10
	s_waitcnt lgkmcnt(0)
	v_mfma_f32_16x16x32_bf16 v[110:113], v[186:189], v[198:201], v[110:113]
	global_load_lds_dwordx4 v[6:7], off
	v_lshl_add_u64 v[6:7], v[132:133], 1, s[28:29]
	s_mov_b32 m0, s11
	v_mfma_f32_16x16x32_bf16 v[18:21], v[206:209], v[198:201], v[18:21]
	global_load_lds_dwordx4 v[6:7], off
	v_lshl_add_u64 v[6:7], v[16:17], 0, s[34:35]
	s_mov_b32 m0, s12
	v_mfma_f32_16x16x32_bf16 v[178:181], v[186:189], v[226:229], v[178:181]
	global_load_lds_dwordx4 v[6:7], off
	v_mfma_f32_16x16x32_bf16 v[2:5], v[186:189], v[230:233], v[182:185]
	v_mfma_f32_16x16x32_bf16 v[6:9], v[186:189], v[234:237], v[106:109]
	ds_read_b128 v[10:13], v164
	ds_read_b128 v[14:17], v164 offset:2048
	s_nop 0
	ds_read_b128 v[106:109], v164 offset:4096
	ds_read_b128 v[182:185], v164 offset:6144
	ds_read_b128 v[186:189], v165 offset:32768
	ds_read_b128 v[190:193], v165 offset:34816
	ds_read_b128 v[194:197], v165 offset:36864
	ds_read_b128 v[198:201], v165 offset:38912
	v_mfma_f32_16x16x32_bf16 v[22:25], v[206:209], v[226:229], v[22:25]
	v_mfma_f32_16x16x32_bf16 v[26:29], v[206:209], v[230:233], v[26:29]
	v_mfma_f32_16x16x32_bf16 v[30:33], v[206:209], v[234:237], v[30:33]
	s_waitcnt lgkmcnt(0)
	v_mfma_f32_16x16x32_bf16 v[50:53], v[186:189], v[10:13], v[50:53]
	v_mfma_f32_16x16x32_bf16 v[58:61], v[186:189], v[14:17], v[58:61]
	v_mfma_f32_16x16x32_bf16 v[66:69], v[186:189], v[106:109], v[66:69]
	v_mfma_f32_16x16x32_bf16 v[34:37], v[186:189], v[182:185], v[34:37]
	ds_read_b128 v[186:189], v165 offset:40960
	ds_read_b128 v[202:205], v165 offset:43008
	v_mfma_f32_16x16x32_bf16 v[54:57], v[190:193], v[10:13], v[54:57]
	v_mfma_f32_16x16x32_bf16 v[62:65], v[190:193], v[14:17], v[62:65]
	v_mfma_f32_16x16x32_bf16 v[70:73], v[190:193], v[106:109], v[70:73]
	v_mfma_f32_16x16x32_bf16 v[38:41], v[190:193], v[182:185], v[38:41]
	v_mfma_f32_16x16x32_bf16 v[82:85], v[194:197], v[10:13], v[82:85]
	v_mfma_f32_16x16x32_bf16 v[90:93], v[194:197], v[14:17], v[90:93]
	v_mfma_f32_16x16x32_bf16 v[98:101], v[194:197], v[106:109], v[98:101]
	v_mfma_f32_16x16x32_bf16 v[42:45], v[194:197], v[182:185], v[42:45]
	ds_read_b128 v[190:193], v165 offset:45056
	ds_read_b128 v[194:197], v165 offset:47104
	v_mfma_f32_16x16x32_bf16 v[86:89], v[198:201], v[10:13], v[86:89]
	v_mfma_f32_16x16x32_bf16 v[94:97], v[198:201], v[14:17], v[94:97]
	v_mfma_f32_16x16x32_bf16 v[102:105], v[198:201], v[106:109], v[102:105]
	v_mfma_f32_16x16x32_bf16 v[46:49], v[198:201], v[182:185], v[46:49]
	s_waitcnt lgkmcnt(0)
	v_mfma_f32_16x16x32_bf16 v[114:117], v[186:189], v[10:13], v[114:117]
	ds_read_b128 v[198:201], v166 offset:32768
	ds_read_b128 v[206:209], v166 offset:34816
	v_mfma_f32_16x16x32_bf16 v[122:125], v[186:189], v[14:17], v[122:125]
	v_mfma_f32_16x16x32_bf16 v[134:137], v[186:189], v[106:109], v[134:137]
	v_mfma_f32_16x16x32_bf16 v[74:77], v[186:189], v[182:185], v[74:77]
	ds_read_b128 v[186:189], v167
	ds_read_b128 v[210:213], v167 offset:2048
	ds_read_b128 v[214:217], v167 offset:4096
	ds_read_b128 v[218:221], v167 offset:6144
	v_mfma_f32_16x16x32_bf16 v[118:121], v[202:205], v[10:13], v[118:121]
	v_mfma_f32_16x16x32_bf16 v[126:129], v[202:205], v[14:17], v[126:129]
	v_mfma_f32_16x16x32_bf16 v[78:81], v[202:205], v[182:185], v[78:81]
	v_mfma_f32_16x16x32_bf16 v[174:177], v[202:205], v[106:109], v[174:177]
	v_mfma_f32_16x16x32_bf16 v[110:113], v[190:193], v[10:13], v[110:113]
	v_mfma_f32_16x16x32_bf16 v[10:13], v[194:197], v[10:13], v[18:21]
	v_mfma_f32_16x16x32_bf16 v[18:21], v[190:193], v[14:17], v[178:181]
	v_mfma_f32_16x16x32_bf16 v[14:17], v[194:197], v[14:17], v[22:25]
	v_mfma_f32_16x16x32_bf16 v[2:5], v[190:193], v[106:109], v[2:5]
	v_mfma_f32_16x16x32_bf16 v[22:25], v[194:197], v[106:109], v[26:29]
	s_nop 2
	ds_read_b128 v[26:29], v166 offset:36864
	ds_read_b128 v[106:109], v166 offset:38912
	v_mfma_f32_16x16x32_bf16 v[6:9], v[190:193], v[182:185], v[6:9]
	v_mfma_f32_16x16x32_bf16 v[30:33], v[194:197], v[182:185], v[30:33]
	ds_read_b128 v[178:181], v166 offset:40960
	ds_read_b128 v[182:185], v166 offset:43008
	s_waitcnt lgkmcnt(0)
	v_mfma_f32_16x16x32_bf16 v[50:53], v[198:201], v[186:189], v[50:53]
	v_mfma_f32_16x16x32_bf16 v[54:57], v[206:209], v[186:189], v[54:57]
	v_mfma_f32_16x16x32_bf16 v[58:61], v[198:201], v[210:213], v[58:61]
	v_mfma_f32_16x16x32_bf16 v[62:65], v[206:209], v[210:213], v[62:65]
	v_mfma_f32_16x16x32_bf16 v[66:69], v[198:201], v[214:217], v[66:69]
	v_mfma_f32_16x16x32_bf16 v[70:73], v[206:209], v[214:217], v[70:73]
	v_mfma_f32_16x16x32_bf16 v[34:37], v[198:201], v[218:221], v[34:37]
	v_mfma_f32_16x16x32_bf16 v[38:41], v[206:209], v[218:221], v[38:41]
	v_mfma_f32_16x16x32_bf16 v[82:85], v[26:29], v[186:189], v[82:85]
	v_mfma_f32_16x16x32_bf16 v[90:93], v[26:29], v[210:213], v[90:93]
	v_mfma_f32_16x16x32_bf16 v[98:101], v[26:29], v[214:217], v[98:101]
	v_mfma_f32_16x16x32_bf16 v[26:29], v[26:29], v[218:221], v[42:45]
	s_nop 2
	ds_read_b128 v[42:45], v166 offset:45056
	ds_read_b128 v[190:193], v166 offset:47104
	v_mfma_f32_16x16x32_bf16 v[86:89], v[106:109], v[186:189], v[86:89]
	v_mfma_f32_16x16x32_bf16 v[94:97], v[106:109], v[210:213], v[94:97]
	v_mfma_f32_16x16x32_bf16 v[102:105], v[106:109], v[214:217], v[102:105]
	v_mfma_f32_16x16x32_bf16 v[46:49], v[106:109], v[218:221], v[46:49]
	v_mfma_f32_16x16x32_bf16 v[106:109], v[178:181], v[186:189], v[114:117]
	v_mfma_f32_16x16x32_bf16 v[114:117], v[182:185], v[186:189], v[118:121]
	v_mfma_f32_16x16x32_bf16 v[118:121], v[178:181], v[210:213], v[122:125]
	v_mfma_f32_16x16x32_bf16 v[122:125], v[182:185], v[210:213], v[126:129]
	v_mfma_f32_16x16x32_bf16 v[126:129], v[178:181], v[214:217], v[134:137]
	v_mfma_f32_16x16x32_bf16 v[134:137], v[182:185], v[214:217], v[174:177]
	v_mfma_f32_16x16x32_bf16 v[74:77], v[178:181], v[218:221], v[74:77]
	v_mfma_f32_16x16x32_bf16 v[78:81], v[182:185], v[218:221], v[78:81]
	s_waitcnt vmcnt(0)
	s_barrier
; template <bool SWAP, class Epi, bool THIN = false> ...
;     ...
;     for (int st = 0; st < ns; ++st) {
;       asm volatile("s_waitcnt vmcnt(0)" ::: "memory");
;       __builtin_amdgcn_s_barrier();
;       asm volatile("" ::: "memory");
;       if (st + 1 < ns) {
;         char* nb = smem + ((st + 1) & 1) * 65536;
;         const int ko = (st + 1) * 64;
; #pragma unroll
;         for (int i = 0; i < 4; ++i) { GLDS16(A + (size_t)(ap[i] + ko), nb + tid * 16 + i * 8192); GLDS16(Bt + (size_t)(bp[i] + ko), nb + 32768 + tid * 16 + i * 8192); }
;       }
;       const char* sa = smem + (st & 1) * 65536 + (wr * 64 + fr) * 128;
;       const char* sb = smem + (st & 1) * 65536 + 32768 + (wc * 128 + fr) * 128;
;       if constexpr (THIN) {
;         if (wc == 0) {
; #pragma unroll
;           for (int ks = 0; ks < 2; ++ks) {
;             bf16x8 af[4], bf[2];
; #pragma unroll
;             for (int m = 0; m < 4; ++m) af[m] = *(const bf16x8*)(sa + m * 2048 + (((ks * 4 + fq) ^ swz) << 4));
; #pragma unroll
;             for (int n = 0; n < 2; ++n) bf[n] = *(const bf16x8*)(sb + n * 2048 + (((ks * 4 + fq) ^ swz) << 4));
; #pragma unroll
;             for (int m = 0; m < 4; ++m)
; #pragma unroll
;               for (int n = 0; n < 2; ++n)
;                 acc[m][n] = SWAP ? __builtin_amdgcn_mfma_f32_16x16x32_bf16(bf[n], af[m], acc[m][n], 0, 0, 0)
;                                  : __builtin_amdgcn_mfma_f32_16x16x32_bf16(af[m], bf[n], acc[m][n], 0, 0, 0);
;           }
;         }
;       } else {
;       bf16x8 afA[4], afB[4], bfb[2][2];
; #pragma unroll
;       for (int m = 0; m < 4; ++m) afA[m] = *(const bf16x8*)(sa + m * 2048 + ((fq ^ swz) << 4));
; #pragma unroll
;       for (int n = 0; n < 2; ++n) bfb[0][n] = *(const bf16x8*)(sb + n * 2048 + ((fq ^ swz) << 4));
; #pragma unroll
;       for (int gq = 0; gq < 8; ++gq) {
;         const int ks = gq >> 2, nh = gq & 3;
;         if (gq < 7) {
;           const int ks2 = (gq + 1) >> 2, nh2 = (gq + 1) & 3;
; #pragma unroll
;           for (int n = 0; n < 2; ++n) bfb[(gq + 1) & 1][n] = *(const bf16x8*)(sb + (nh2 * 2 + n) * 2048 + (((ks2 * 4 + fq) ^ swz) << 4));
;         }
;         if (gq == 3) {
; #pragma unroll
;           for (int m = 0; m < 4; ++m) afB[m] = *(const bf16x8*)(sa + m * 2048 + (((4 + fq) ^ swz) << 4));
;         }
;         __builtin_amdgcn_sched_barrier(0);
; #pragma unroll
	s_waitcnt lgkmcnt(0)
	v_mfma_f32_16x16x32_bf16 v[110:113], v[42:45], v[186:189], v[110:113]
	v_mfma_f32_16x16x32_bf16 v[10:13], v[190:193], v[186:189], v[10:13]
	ds_read_b128 v[174:177], v168
	ds_read_b128 v[178:181], v168 offset:2048
	ds_read_b128 v[182:185], v168 offset:4096
	ds_read_b128 v[186:189], v168 offset:6144
	v_mfma_f32_16x16x32_bf16 v[18:21], v[42:45], v[210:213], v[18:21]
	v_mfma_f32_16x16x32_bf16 v[2:5], v[42:45], v[214:217], v[2:5]
	v_mfma_f32_16x16x32_bf16 v[6:9], v[42:45], v[218:221], v[6:9]
	ds_read_b128 v[42:45], v169
	ds_read_b128 v[194:197], v169 offset:2048
	ds_read_b128 v[198:201], v169 offset:4096
	ds_read_b128 v[202:205], v169 offset:6144
	v_mfma_f32_16x16x32_bf16 v[14:17], v[190:193], v[210:213], v[14:17]
	v_mfma_f32_16x16x32_bf16 v[22:25], v[190:193], v[214:217], v[22:25]
	v_mfma_f32_16x16x32_bf16 v[30:33], v[190:193], v[218:221], v[30:33]
	s_waitcnt lgkmcnt(0)
	v_mfma_f32_16x16x32_bf16 v[50:53], v[42:45], v[174:177], v[50:53]
	v_mfma_f32_16x16x32_bf16 v[58:61], v[42:45], v[178:181], v[58:61]
	v_mfma_f32_16x16x32_bf16 v[66:69], v[42:45], v[182:185], v[66:69]
	v_mfma_f32_16x16x32_bf16 v[34:37], v[42:45], v[186:189], v[34:37]
	ds_read_b128 v[42:45], v169 offset:8192
	ds_read_b128 v[190:193], v169 offset:10240
	v_mfma_f32_16x16x32_bf16 v[54:57], v[194:197], v[174:177], v[54:57]
	v_mfma_f32_16x16x32_bf16 v[62:65], v[194:197], v[178:181], v[62:65]
	v_mfma_f32_16x16x32_bf16 v[70:73], v[194:197], v[182:185], v[70:73]
	v_mfma_f32_16x16x32_bf16 v[38:41], v[194:197], v[186:189], v[38:41]
	v_mfma_f32_16x16x32_bf16 v[82:85], v[198:201], v[174:177], v[82:85]
	v_mfma_f32_16x16x32_bf16 v[194:197], v[198:201], v[178:181], v[90:93]
	v_mfma_f32_16x16x32_bf16 v[98:101], v[198:201], v[182:185], v[98:101]
	v_mfma_f32_16x16x32_bf16 v[198:201], v[198:201], v[186:189], v[26:29]
	s_nop 2
	ds_read_b128 v[26:29], v169 offset:12288
	ds_read_b128 v[90:93], v169 offset:14336
	v_mfma_f32_16x16x32_bf16 v[86:89], v[202:205], v[174:177], v[86:89]
	v_mfma_f32_16x16x32_bf16 v[102:105], v[202:205], v[182:185], v[102:105]
	v_mfma_f32_16x16x32_bf16 v[46:49], v[202:205], v[186:189], v[46:49]
	v_mfma_f32_16x16x32_bf16 v[206:209], v[202:205], v[178:181], v[94:97]
	s_waitcnt lgkmcnt(0)
	v_mfma_f32_16x16x32_bf16 v[202:205], v[190:193], v[174:177], v[114:117]
	v_mfma_f32_16x16x32_bf16 v[210:213], v[42:45], v[178:181], v[118:121]
	s_nop 1
	ds_read_b128 v[114:117], v170
	ds_read_b128 v[118:121], v170 offset:2048
	ds_read_b128 v[226:229], v171
	ds_read_b128 v[230:233], v171 offset:2048
	ds_read_b128 v[234:237], v171 offset:4096
	ds_read_b128 v[238:241], v171 offset:6144
	v_mfma_f32_16x16x32_bf16 v[106:109], v[42:45], v[174:177], v[106:109]
	v_mfma_f32_16x16x32_bf16 v[134:137], v[190:193], v[182:185], v[134:137]
	v_mfma_f32_16x16x32_bf16 v[214:217], v[190:193], v[178:181], v[122:125]
	v_mfma_f32_16x16x32_bf16 v[218:221], v[42:45], v[182:185], v[126:129]
	v_mfma_f32_16x16x32_bf16 v[222:225], v[42:45], v[186:189], v[74:77]
	v_mfma_f32_16x16x32_bf16 v[190:193], v[190:193], v[186:189], v[78:81]
	v_mfma_f32_16x16x32_bf16 v[242:245], v[26:29], v[174:177], v[110:113]
	v_mfma_f32_16x16x32_bf16 v[174:177], v[90:93], v[174:177], v[10:13]
	v_mfma_f32_16x16x32_bf16 v[246:249], v[26:29], v[178:181], v[18:21]
	v_mfma_f32_16x16x32_bf16 v[178:181], v[90:93], v[178:181], v[14:17]
	s_nop 0
	ds_read_b128 v[10:13], v170 offset:4096
	s_nop 0
	ds_read_b128 v[14:17], v170 offset:6144
	v_mfma_f32_16x16x32_bf16 v[2:5], v[26:29], v[182:185], v[2:5]
	v_mfma_f32_16x16x32_bf16 v[6:9], v[26:29], v[186:189], v[6:9]
	v_mfma_f32_16x16x32_bf16 v[182:185], v[90:93], v[182:185], v[22:25]
	v_mfma_f32_16x16x32_bf16 v[186:189], v[90:93], v[186:189], v[30:33]
	s_waitcnt lgkmcnt(0)
	v_mfma_f32_16x16x32_bf16 v[90:93], v[118:121], v[230:233], v[62:65]
	v_mfma_f32_16x16x32_bf16 v[62:65], v[114:117], v[234:237], v[66:69]
	v_mfma_f32_16x16x32_bf16 v[30:33], v[114:117], v[238:241], v[34:37]
	s_nop 2
	ds_read_b128 v[34:37], v170 offset:8192
	ds_read_b128 v[66:69], v170 offset:10240
	v_mfma_f32_16x16x32_bf16 v[126:129], v[114:117], v[226:229], v[50:53]
	v_mfma_f32_16x16x32_bf16 v[122:125], v[118:121], v[226:229], v[54:57]
	v_mfma_f32_16x16x32_bf16 v[94:97], v[114:117], v[230:233], v[58:61]
	v_mfma_f32_16x16x32_bf16 v[58:61], v[118:121], v[234:237], v[70:73]
	v_mfma_f32_16x16x32_bf16 v[26:29], v[118:121], v[238:241], v[38:41]
	v_mfma_f32_16x16x32_bf16 v[114:117], v[14:17], v[226:229], v[86:89]
	v_mfma_f32_16x16x32_bf16 v[86:89], v[10:13], v[230:233], v[194:197]
	v_mfma_f32_16x16x32_bf16 v[22:25], v[10:13], v[238:241], v[198:201]
	s_nop 1
	ds_read_b128 v[194:197], v170 offset:12288
	ds_read_b128 v[198:201], v170 offset:14336
	v_mfma_f32_16x16x32_bf16 v[118:121], v[10:13], v[226:229], v[82:85]
	v_mfma_f32_16x16x32_bf16 v[82:85], v[14:17], v[230:233], v[206:209]
	v_mfma_f32_16x16x32_bf16 v[54:57], v[10:13], v[234:237], v[98:101]
	v_mfma_f32_16x16x32_bf16 v[50:53], v[14:17], v[234:237], v[102:105]
	v_mfma_f32_16x16x32_bf16 v[18:21], v[14:17], v[238:241], v[46:49]
	s_waitcnt lgkmcnt(0)
	v_mfma_f32_16x16x32_bf16 v[110:113], v[34:37], v[226:229], v[106:109]
	v_mfma_f32_16x16x32_bf16 v[106:109], v[66:69], v[226:229], v[202:205]
	v_mfma_f32_16x16x32_bf16 v[78:81], v[34:37], v[230:233], v[210:213]
	v_mfma_f32_16x16x32_bf16 v[74:77], v[66:69], v[230:233], v[214:217]
	v_mfma_f32_16x16x32_bf16 v[46:49], v[34:37], v[234:237], v[218:221]
	v_mfma_f32_16x16x32_bf16 v[42:45], v[66:69], v[234:237], v[134:137]
	v_mfma_f32_16x16x32_bf16 v[14:17], v[34:37], v[238:241], v[222:225]
	v_mfma_f32_16x16x32_bf16 v[10:13], v[66:69], v[238:241], v[190:193]
	s_nop 0
	v_mov_b32_e32 v134, v1
	s_waitcnt vmcnt(0)
	s_barrier
; __device__ __forceinline__ int get_tid512() { int t = threadIdx.x; asm volatile("" : "+v"(t)); return t; }
; __device__ __forceinline__ unsigned pack2(float a, float b) { unsigned r; asm("v_cvt_pk_bf16_f32 %0, %1, %2" : "=v"(r) : "v"(a), "v"(b)); return r; }
;   __device__ __forceinline__ void c4(int g, int rig, int col, f32x4 v) const {
;     const size_t row = (size_t)g * ostride + rig;
;     float s = 1.f;
;     if (NP > 0) {
;       float t = 0.f;
; #pragma unroll
;       for (int q = 0; q < NP; ++q) t += part[(size_t)q * pstride + row];
;       s = rsqrtf(t * inv_n + 1e-6f);
;     }
;     uint2 u; u.x = pack2(v[0] * s, v[1] * s); u.y = pack2(v[2] * s, v[3] * s);
;     *(uint2*)(out + row * ld + col) = u;
;   }
; template <bool SWAP, class Epi, bool THIN = false> ...
;     ...
;     const int te = get_tid512();
;     const int fr_e = te & 15, fq_e = (te & 63) >> 4, wr_e = te >> 7, wc_e = (te >> 6) & 1;
;     const int sub = 2 * mt + (wr_e >> 1);
;     const int g = sub / tpg, ti = sub - g * tpg;
;     const int rig0 = ti * step - halo;
;     const int rw = (wr_e & 1) * 64;
;     if constexpr (Epi::KIND == 0) {
; #pragma unroll
;       for (int m = 0; m < 4; ++m) {
;         const int rig = rig0 + rw + m * 16 + fr_e;
;         if constexpr (Epi::ROWSUM) {
;           float ss = 0.f;
; #pragma unroll
;           for (int n = 0; n < 8; ++n) {
;             const int col = nt * 256 + wc_e * 128 + n * 16 + fq_e * 4;
;             if (col < N) ss += epi.c4(g, rig, col, acc[m][n]);
;           }
;           ss += __shfl_xor(ss, 16); ss += __shfl_xor(ss, 32);
;           if (fq_e == 0) epi.rowsum(g, rig, nt * 2 + wc_e, ss);
;         } else {
; #pragma unroll
;           for (int n = 0; n < 8; ++n) {
;             const int col = nt * 256 + wc_e * 128 + n * 16 + fq_e * 4;
;             if (col < N) epi.c4(g, rig, col, acc[m][n]);
;           }
	v_mfma_f32_16x16x32_bf16 v[38:41], v[194:197], v[234:237], v[2:5]
	v_ashrrev_i32_e32 v35, 8, v134
	v_add_u32_e32 v35, s5, v35
	v_mul_hi_i32 v36, v35, s42
	v_lshrrev_b32_e32 v37, 31, v36
	v_ashrrev_i32_e32 v36, 2, v36
	v_add_u32_e32 v132, v36, v37
	v_mul_lo_u32 v36, v132, s43
	v_lshrrev_b32_e32 v2, 1, v134
	v_and_b32_e32 v34, 15, v134
	v_add_lshl_u32 v35, v36, v35, 7
	v_and_b32_e32 v2, 64, v2
	v_or3_b32 v136, v35, v2, v34
	v_lshlrev_b32_e32 v2, 1, v134
	v_lshrrev_b32_e32 v3, 2, v134
	v_and_b32_e32 v2, 0x80, v2
	v_and_b32_e32 v3, 12, v3
	v_mfma_f32_16x16x32_bf16 v[102:105], v[194:197], v[226:229], v[242:245]
	v_or3_b32 v134, v3, v2, s4
	v_bfe_u32 v252, v1, 4, 1
	v_mul_u32_u24_e32 v252, 24, v252
	v_mov_b32_e32 v253, 0
	v_ashrrev_i32_e32 v137, 31, v136
	v_cmp_gt_i32_e64 s[10:11], s46, v134
	v_mfma_f32_16x16x32_bf16 v[98:101], v[198:201], v[226:229], v[174:177]
	v_ashrrev_i32_e32 v135, 31, v134
	v_mfma_f32_16x16x32_bf16 v[70:73], v[194:197], v[230:233], v[246:249]
	v_mfma_f32_16x16x32_bf16 v[66:69], v[198:201], v[230:233], v[178:181]
	v_mfma_f32_16x16x32_bf16 v[34:37], v[198:201], v[234:237], v[182:185]
	v_mfma_f32_16x16x32_bf16 v[6:9], v[194:197], v[238:241], v[6:9]
	v_mfma_f32_16x16x32_bf16 v[2:5], v[198:201], v[238:241], v[186:189]
	v_mad_i64_i32 v[174:175], s[6:7], v132, s44, v[136:137]
	v_lshl_add_u64 v[176:177], v[174:175], 2, s[26:27]
	v_add_co_u32_e32 v178, vcc, 0x12000, v176
	v_lshlrev_b64 v[174:175], 11, v[174:175]
	s_nop 0
	v_addc_co_u32_e32 v179, vcc, 0, v177, vcc
	global_load_dword v173, v[176:177], off
	s_nop 0
	global_load_dword v204, v[176:177], off offset:64
	global_load_dword v205, v[178:179], off offset:64
	global_load_dword v206, v[176:177], off offset:128
	global_load_dword v207, v[178:179], off offset:128
	global_load_dword v208, v[176:177], off offset:192
	global_load_dword v209, v[178:179], off offset:192
	global_load_dword v176, v[178:179], off
	v_lshl_add_u64 v[174:175], s[22:23], 0, v[174:175]
	s_waitcnt vmcnt(0)
	v_add_f32_e32 v173, 0, v173
	v_add_f32_e32 v173, v173, v176
	v_fmamk_f32 v173, v173, 0x3b800000, v172
	v_mul_f32_e32 v176, 0x4b800000, v173
	v_cmp_gt_f32_e32 vcc, s47, v173
	s_nop 1
	v_cndmask_b32_e32 v173, v173, v176, vcc
	v_rsq_f32_e32 v173, v173
	s_nop 0
	v_mul_f32_e32 v176, 0x45800000, v173
	v_cndmask_b32_e32 v173, v173, v176, vcc
	v_mov_b32_e32 v251, v173
	v_mul_f32_e32 v126, v126, v173
	v_mul_f32_e32 v127, v127, v173
	v_mul_f32_e32 v128, v128, v173
	v_mul_f32_e32 v129, v129, v173
	v_cvt_pk_bf16_f32 v126, v126, v127
	v_cvt_pk_bf16_f32 v127, v128, v129
	v_or_b32_e32 v254, 16, v134
	v_mad_i64_i32 v[254:255], s[6:7], v132, s44, v[136:137]
	v_lshlrev_b64 v[254:255], 11, v[254:255]
	s_nop 0
	v_lshl_add_u64 v[254:255], s[22:23], 0, v[254:255]
	v_mul_f32_e32 v122, v122, v251
	v_mul_f32_e32 v123, v123, v251
	v_mul_f32_e32 v124, v124, v251
	v_mul_f32_e32 v125, v125, v251
	v_cvt_pk_bf16_f32 v128, v122, v123
	v_cvt_pk_bf16_f32 v129, v124, v125
	v_lshl_add_u64 v[124:125], v[134:135], 1, v[254:255]
	s_nop 1
	v_permlane16_swap_b32 v126, v128
	v_permlane16_swap_b32 v127, v129
	v_lshl_add_u64 v[254:255], v[124:125], 0, v[252:253]
	s_nop 0
	global_store_dwordx4 v[254:255], v[126:129], off
	s_nop 1
	v_or_b32_e32 v122, 32, v134
	v_mad_i64_i32 v[122:123], s[6:7], v132, s44, v[136:137]
	v_lshlrev_b64 v[122:123], 11, v[122:123]
	s_nop 0
	v_lshl_add_u64 v[122:123], s[22:23], 0, v[122:123]
	v_mul_f32_e32 v118, v118, v251
	v_mul_f32_e32 v119, v119, v251
	v_mul_f32_e32 v120, v120, v251
	v_mul_f32_e32 v121, v121, v251
	v_cvt_pk_bf16_f32 v118, v118, v119
	v_cvt_pk_bf16_f32 v119, v120, v121
	v_or_b32_e32 v254, 48, v134
	v_mad_i64_i32 v[254:255], s[6:7], v132, s44, v[136:137]
	v_lshlrev_b64 v[254:255], 11, v[254:255]
	s_nop 0
	v_lshl_add_u64 v[254:255], s[22:23], 0, v[254:255]
	v_mul_f32_e32 v114, v114, v251
	v_mul_f32_e32 v115, v115, v251
	v_mul_f32_e32 v116, v116, v251
	v_mul_f32_e32 v117, v117, v251
	v_cvt_pk_bf16_f32 v120, v114, v115
	v_cvt_pk_bf16_f32 v121, v116, v117
	v_lshl_add_u64 v[116:117], v[134:135], 1, v[254:255]
	s_nop 1
	v_permlane16_swap_b32 v118, v120
	v_permlane16_swap_b32 v119, v121
	v_lshl_add_u64 v[254:255], v[116:117], 0, v[252:253]
	s_nop 0
	global_store_dwordx4 v[254:255], v[118:121], off offset:64
	s_nop 1
	v_or_b32_e32 v114, 64, v134
	v_mad_i64_i32 v[114:115], s[6:7], v132, s44, v[136:137]
	v_lshlrev_b64 v[114:115], 11, v[114:115]
	s_nop 0
	v_lshl_add_u64 v[114:115], s[22:23], 0, v[114:115]
	v_mul_f32_e32 v110, v110, v251
	v_mul_f32_e32 v111, v111, v251
	v_mul_f32_e32 v112, v112, v251
	v_mul_f32_e32 v113, v113, v251
	v_cvt_pk_bf16_f32 v110, v110, v111
	v_cvt_pk_bf16_f32 v111, v112, v113
	v_or_b32_e32 v254, 0x50, v134
	v_mad_i64_i32 v[254:255], s[6:7], v132, s44, v[136:137]
	v_lshlrev_b64 v[254:255], 11, v[254:255]
	s_nop 0
	v_lshl_add_u64 v[254:255], s[22:23], 0, v[254:255]
	v_mul_f32_e32 v106, v106, v251
	v_mul_f32_e32 v107, v107, v251
	v_mul_f32_e32 v108, v108, v251
	v_mul_f32_e32 v109, v109, v251
	v_cvt_pk_bf16_f32 v112, v106, v107
	v_cvt_pk_bf16_f32 v113, v108, v109
	v_lshl_add_u64 v[108:109], v[134:135], 1, v[254:255]
	s_nop 1
	v_permlane16_swap_b32 v110, v112
	v_permlane16_swap_b32 v111, v113
	v_lshl_add_u64 v[254:255], v[108:109], 0, v[252:253]
	s_nop 0
	global_store_dwordx4 v[254:255], v[110:113], off offset:128
	s_nop 1
	v_or_b32_e32 v106, 0x60, v134
	v_mad_i64_i32 v[106:107], s[36:37], v132, s44, v[136:137]
	v_lshlrev_b64 v[106:107], 11, v[106:107]
	s_nop 0
	v_lshl_add_u64 v[106:107], s[22:23], 0, v[106:107]
	v_mul_f32_e32 v102, v102, v251
	v_mul_f32_e32 v103, v103, v251
	v_mul_f32_e32 v104, v104, v251
	v_mul_f32_e32 v105, v105, v251
	v_cvt_pk_bf16_f32 v102, v102, v103
	v_cvt_pk_bf16_f32 v103, v104, v105
; __device__ __forceinline__ int get_tid512() { int t = threadIdx.x; asm volatile("" : "+v"(t)); return t; }
; __device__ __forceinline__ unsigned pack2(float a, float b) { unsigned r; asm("v_cvt_pk_bf16_f32 %0, %1, %2" : "=v"(r) : "v"(a), "v"(b)); return r; }
;   __device__ __forceinline__ void c4(int g, int rig, int col, f32x4 v) const {
;     const size_t row = (size_t)g * ostride + rig;
;     float s = 1.f;
;     if (NP > 0) {
;       float t = 0.f;
; #pragma unroll
;       for (int q = 0; q < NP; ++q) t += part[(size_t)q * pstride + row];
;       s = rsqrtf(t * inv_n + 1e-6f);
;     }
;     uint2 u; u.x = pack2(v[0] * s, v[1] * s); u.y = pack2(v[2] * s, v[3] * s);
;     *(uint2*)(out + row * ld + col) = u;
;   }
; template <bool SWAP, class Epi, bool THIN = false> ...
;     ...
;     const int te = get_tid512();
;     const int fr_e = te & 15, fq_e = (te & 63) >> 4, wr_e = te >> 7, wc_e = (te >> 6) & 1;
;     const int sub = 2 * mt + (wr_e >> 1);
;     const int g = sub / tpg, ti = sub - g * tpg;
;     const int rig0 = ti * step - halo;
;     const int rw = (wr_e & 1) * 64;
;     if constexpr (Epi::KIND == 0) {
; #pragma unroll
;       for (int m = 0; m < 4; ++m) {
;         const int rig = rig0 + rw + m * 16 + fr_e;
;         if constexpr (Epi::ROWSUM) {
;           float ss = 0.f;
; #pragma unroll
;           for (int n = 0; n < 8; ++n) {
;             const int col = nt * 256 + wc_e * 128 + n * 16 + fq_e * 4;
;             if (col < N) ss += epi.c4(g, rig, col, acc[m][n]);
;           }
;           ss += __shfl_xor(ss, 16); ss += __shfl_xor(ss, 32);
;           if (fq_e == 0) epi.rowsum(g, rig, nt * 2 + wc_e, ss);
;         } else {
; #pragma unroll
;           for (int n = 0; n < 8; ++n) {
;             const int col = nt * 256 + wc_e * 128 + n * 16 + fq_e * 4;
;             if (col < N) epi.c4(g, rig, col, acc[m][n]);
;           }
	v_or_b32_e32 v254, 0x70, v134
	v_mad_i64_i32 v[254:255], s[48:49], v132, s44, v[136:137]
	v_lshlrev_b64 v[254:255], 11, v[254:255]
	s_nop 0
	v_lshl_add_u64 v[254:255], s[22:23], 0, v[254:255]
	v_mul_f32_e32 v98, v98, v251
	v_mul_f32_e32 v99, v99, v251
	v_mul_f32_e32 v100, v100, v251
	v_mul_f32_e32 v101, v101, v251
	v_cvt_pk_bf16_f32 v104, v98, v99
	v_cvt_pk_bf16_f32 v105, v100, v101
	v_lshl_add_u64 v[100:101], v[134:135], 1, v[254:255]
	s_nop 1
	v_permlane16_swap_b32 v102, v104
	v_permlane16_swap_b32 v103, v105
	v_lshl_add_u64 v[254:255], v[100:101], 0, v[252:253]
	s_nop 0
	global_store_dwordx4 v[254:255], v[102:105], off offset:192
	s_nop 1
	v_or_b32_e32 v98, 16, v136
	v_ashrrev_i32_e32 v99, 31, v98
	v_mad_i64_i32 v[100:101], s[48:49], v132, s44, v[136:137]
	v_lshl_add_u64 v[100:101], v[100:101], 2, s[26:27]
	v_add_co_u32_e32 v102, vcc, 0x12000, v100
	s_nop 1
	v_addc_co_u32_e32 v103, vcc, 0, v101, vcc
	s_nop 0
	v_add_f32_e32 v100, 0, v204
	v_add_f32_e32 v100, v100, v205
	v_fmamk_f32 v100, v100, 0x3b800000, v172
	v_mul_f32_e32 v101, 0x4b800000, v100
	v_cmp_gt_f32_e32 vcc, s47, v100
	s_nop 1
	v_cndmask_b32_e32 v100, v100, v101, vcc
	v_rsq_f32_e32 v102, v100
	v_mad_i64_i32 v[100:101], s[48:49], v132, s44, v[98:99]
	v_lshlrev_b64 v[100:101], 11, v[100:101]
	v_mul_f32_e32 v103, 0x45800000, v102
	v_cndmask_b32_e32 v102, v102, v103, vcc
	v_lshl_add_u64 v[100:101], s[22:23], 0, v[100:101]
	v_mov_b32_e32 v251, v102
	v_mul_f32_e32 v94, v94, v102
	v_mul_f32_e32 v95, v95, v102
	v_mul_f32_e32 v96, v96, v102
	v_mul_f32_e32 v97, v97, v102
	v_cvt_pk_bf16_f32 v94, v94, v95
	v_cvt_pk_bf16_f32 v95, v96, v97
	v_mad_i64_i32 v[254:255], s[48:49], v132, s44, v[98:99]
	v_lshlrev_b64 v[254:255], 11, v[254:255]
	v_lshl_add_u64 v[254:255], s[22:23], 0, v[254:255]
	v_mul_f32_e32 v90, v90, v251
	v_mul_f32_e32 v91, v91, v251
	v_mul_f32_e32 v92, v92, v251
	v_mul_f32_e32 v93, v93, v251
	v_cvt_pk_bf16_f32 v96, v90, v91
	v_cvt_pk_bf16_f32 v97, v92, v93
	v_lshl_add_u64 v[92:93], v[134:135], 1, v[254:255]
	s_nop 1
	v_permlane16_swap_b32 v94, v96
	v_permlane16_swap_b32 v95, v97
	v_lshl_add_u64 v[254:255], v[92:93], 0, v[252:253]
	s_nop 0
	global_store_dwordx4 v[254:255], v[94:97], off
	s_nop 1
	v_mad_i64_i32 v[90:91], s[48:49], v132, s44, v[98:99]
	v_lshlrev_b64 v[90:91], 11, v[90:91]
	v_lshl_add_u64 v[90:91], s[22:23], 0, v[90:91]
	v_mul_f32_e32 v86, v86, v251
	v_mul_f32_e32 v87, v87, v251
	v_mul_f32_e32 v88, v88, v251
	v_mul_f32_e32 v89, v89, v251
	v_cvt_pk_bf16_f32 v86, v86, v87
	v_cvt_pk_bf16_f32 v87, v88, v89
	v_mad_i64_i32 v[254:255], s[48:49], v132, s44, v[98:99]
	v_lshlrev_b64 v[254:255], 11, v[254:255]
	v_lshl_add_u64 v[254:255], s[22:23], 0, v[254:255]
	v_mul_f32_e32 v82, v82, v251
	v_mul_f32_e32 v83, v83, v251
	v_mul_f32_e32 v84, v84, v251
	v_mul_f32_e32 v85, v85, v251
	v_cvt_pk_bf16_f32 v88, v82, v83
	v_cvt_pk_bf16_f32 v89, v84, v85
	v_lshl_add_u64 v[84:85], v[134:135], 1, v[254:255]
	s_nop 1
	v_permlane16_swap_b32 v86, v88
	v_permlane16_swap_b32 v87, v89
	v_lshl_add_u64 v[254:255], v[84:85], 0, v[252:253]
	s_nop 0
	global_store_dwordx4 v[254:255], v[86:89], off offset:64
	s_nop 1
	v_mad_i64_i32 v[82:83], s[48:49], v132, s44, v[98:99]
	v_lshlrev_b64 v[82:83], 11, v[82:83]
	v_lshl_add_u64 v[82:83], s[22:23], 0, v[82:83]
	v_mul_f32_e32 v78, v78, v251
	v_mul_f32_e32 v79, v79, v251
	v_mul_f32_e32 v80, v80, v251
	v_mul_f32_e32 v81, v81, v251
	v_cvt_pk_bf16_f32 v78, v78, v79
	v_cvt_pk_bf16_f32 v79, v80, v81
	v_mad_i64_i32 v[254:255], s[48:49], v132, s44, v[98:99]
	v_lshlrev_b64 v[254:255], 11, v[254:255]
	v_lshl_add_u64 v[254:255], s[22:23], 0, v[254:255]
	v_mul_f32_e32 v74, v74, v251
	v_mul_f32_e32 v75, v75, v251
	v_mul_f32_e32 v76, v76, v251
	v_mul_f32_e32 v77, v77, v251
	v_cvt_pk_bf16_f32 v80, v74, v75
	v_cvt_pk_bf16_f32 v81, v76, v77
	v_lshl_add_u64 v[76:77], v[134:135], 1, v[254:255]
	s_nop 1
	v_permlane16_swap_b32 v78, v80
	v_permlane16_swap_b32 v79, v81
	v_lshl_add_u64 v[254:255], v[76:77], 0, v[252:253]
	s_nop 0
	global_store_dwordx4 v[254:255], v[78:81], off offset:128
	s_nop 1
	v_mad_i64_i32 v[74:75], s[48:49], v132, s44, v[98:99]
	v_lshlrev_b64 v[74:75], 11, v[74:75]
	v_lshl_add_u64 v[74:75], s[22:23], 0, v[74:75]
	v_mul_f32_e32 v70, v70, v251
	v_mul_f32_e32 v71, v71, v251
	v_mul_f32_e32 v72, v72, v251
	v_mul_f32_e32 v73, v73, v251
	v_cvt_pk_bf16_f32 v70, v70, v71
	v_cvt_pk_bf16_f32 v71, v72, v73
	v_mad_i64_i32 v[254:255], s[48:49], v132, s44, v[98:99]
	v_lshlrev_b64 v[254:255], 11, v[254:255]
	v_lshl_add_u64 v[254:255], s[22:23], 0, v[254:255]
	v_mul_f32_e32 v66, v66, v251
	v_mul_f32_e32 v67, v67, v251
	v_mul_f32_e32 v68, v68, v251
	v_mul_f32_e32 v69, v69, v251
	v_cvt_pk_bf16_f32 v72, v66, v67
	v_cvt_pk_bf16_f32 v73, v68, v69
	v_lshl_add_u64 v[68:69], v[134:135], 1, v[254:255]
	s_nop 1
	v_permlane16_swap_b32 v70, v72
	v_permlane16_swap_b32 v71, v73
	v_lshl_add_u64 v[254:255], v[68:69], 0, v[252:253]
	s_nop 0
	global_store_dwordx4 v[254:255], v[70:73], off offset:192
	s_nop 1
	v_or_b32_e32 v66, 32, v136
	v_ashrrev_i32_e32 v67, 31, v66
	v_mad_i64_i32 v[68:69], s[48:49], v132, s44, v[136:137]
	v_lshl_add_u64 v[68:69], v[68:69], 2, s[26:27]
	v_add_co_u32_e32 v70, vcc, 0x12000, v68
	s_nop 1
	v_addc_co_u32_e32 v71, vcc, 0, v69, vcc
	s_nop 0
	v_add_f32_e32 v68, 0, v206
	v_add_f32_e32 v68, v68, v207
	v_fmamk_f32 v68, v68, 0x3b800000, v172
	v_mul_f32_e32 v69, 0x4b800000, v68
	v_cmp_gt_f32_e32 vcc, s47, v68
	s_nop 1
	v_cndmask_b32_e32 v68, v68, v69, vcc
	v_rsq_f32_e32 v70, v68
	v_mad_i64_i32 v[68:69], s[48:49], v132, s44, v[66:67]
	v_lshlrev_b64 v[68:69], 11, v[68:69]
	v_mul_f32_e32 v71, 0x45800000, v70
	v_cndmask_b32_e32 v70, v70, v71, vcc
; __device__ __forceinline__ int get_tid512() { int t = threadIdx.x; asm volatile("" : "+v"(t)); return t; }
; __device__ __forceinline__ unsigned pack2(float a, float b) { unsigned r; asm("v_cvt_pk_bf16_f32 %0, %1, %2" : "=v"(r) : "v"(a), "v"(b)); return r; }
;   __device__ __forceinline__ void c4(int g, int rig, int col, f32x4 v) const {
;     const size_t row = (size_t)g * ostride + rig;
;     float s = 1.f;
;     if (NP > 0) {
;       float t = 0.f;
; #pragma unroll
;       for (int q = 0; q < NP; ++q) t += part[(size_t)q * pstride + row];
;       s = rsqrtf(t * inv_n + 1e-6f);
;     }
;     uint2 u; u.x = pack2(v[0] * s, v[1] * s); u.y = pack2(v[2] * s, v[3] * s);
;     *(uint2*)(out + row * ld + col) = u;
;   }
; template <bool SWAP, class Epi, bool THIN = false> ...
;     ...
;     const int te = get_tid512();
;     const int fr_e = te & 15, fq_e = (te & 63) >> 4, wr_e = te >> 7, wc_e = (te >> 6) & 1;
;     const int sub = 2 * mt + (wr_e >> 1);
;     const int g = sub / tpg, ti = sub - g * tpg;
;     const int rig0 = ti * step - halo;
;     const int rw = (wr_e & 1) * 64;
;     if constexpr (Epi::KIND == 0) {
; #pragma unroll
;       for (int m = 0; m < 4; ++m) {
;         const int rig = rig0 + rw + m * 16 + fr_e;
;         if constexpr (Epi::ROWSUM) {
;           float ss = 0.f;
; #pragma unroll
;           for (int n = 0; n < 8; ++n) {
;             const int col = nt * 256 + wc_e * 128 + n * 16 + fq_e * 4;
;             if (col < N) ss += epi.c4(g, rig, col, acc[m][n]);
;           }
;           ss += __shfl_xor(ss, 16); ss += __shfl_xor(ss, 32);
;           if (fq_e == 0) epi.rowsum(g, rig, nt * 2 + wc_e, ss);
;         } else {
; #pragma unroll
;           for (int n = 0; n < 8; ++n) {
;             const int col = nt * 256 + wc_e * 128 + n * 16 + fq_e * 4;
;             if (col < N) epi.c4(g, rig, col, acc[m][n]);
;           }
	v_lshl_add_u64 v[68:69], s[22:23], 0, v[68:69]
	v_mov_b32_e32 v251, v70
	v_mul_f32_e32 v62, v62, v70
	v_mul_f32_e32 v63, v63, v70
	v_mul_f32_e32 v64, v64, v70
	v_mul_f32_e32 v65, v65, v70
	v_cvt_pk_bf16_f32 v62, v62, v63
	v_cvt_pk_bf16_f32 v63, v64, v65
	v_mad_i64_i32 v[254:255], s[48:49], v132, s44, v[66:67]
	v_lshlrev_b64 v[254:255], 11, v[254:255]
	v_lshl_add_u64 v[254:255], s[22:23], 0, v[254:255]
	v_mul_f32_e32 v58, v58, v251
	v_mul_f32_e32 v59, v59, v251
	v_mul_f32_e32 v60, v60, v251
	v_mul_f32_e32 v61, v61, v251
	v_cvt_pk_bf16_f32 v64, v58, v59
	v_cvt_pk_bf16_f32 v65, v60, v61
	v_lshl_add_u64 v[60:61], v[134:135], 1, v[254:255]
	s_nop 1
	v_permlane16_swap_b32 v62, v64
	v_permlane16_swap_b32 v63, v65
	v_lshl_add_u64 v[254:255], v[60:61], 0, v[252:253]
	s_nop 0
	global_store_dwordx4 v[254:255], v[62:65], off
	s_nop 1
	v_mad_i64_i32 v[58:59], s[48:49], v132, s44, v[66:67]
	v_lshlrev_b64 v[58:59], 11, v[58:59]
	v_lshl_add_u64 v[58:59], s[22:23], 0, v[58:59]
	v_mul_f32_e32 v54, v54, v251
	v_mul_f32_e32 v55, v55, v251
	v_mul_f32_e32 v56, v56, v251
	v_mul_f32_e32 v57, v57, v251
	v_cvt_pk_bf16_f32 v54, v54, v55
	v_cvt_pk_bf16_f32 v55, v56, v57
	v_mad_i64_i32 v[254:255], s[48:49], v132, s44, v[66:67]
	v_lshlrev_b64 v[254:255], 11, v[254:255]
	v_lshl_add_u64 v[254:255], s[22:23], 0, v[254:255]
	v_mul_f32_e32 v50, v50, v251
	v_mul_f32_e32 v51, v51, v251
	v_mul_f32_e32 v52, v52, v251
	v_mul_f32_e32 v53, v53, v251
	v_cvt_pk_bf16_f32 v56, v50, v51
	v_cvt_pk_bf16_f32 v57, v52, v53
	v_lshl_add_u64 v[52:53], v[134:135], 1, v[254:255]
	s_nop 1
	v_permlane16_swap_b32 v54, v56
	v_permlane16_swap_b32 v55, v57
	v_lshl_add_u64 v[254:255], v[52:53], 0, v[252:253]
	s_nop 0
	global_store_dwordx4 v[254:255], v[54:57], off offset:64
	s_nop 1
	v_mad_i64_i32 v[50:51], s[48:49], v132, s44, v[66:67]
	v_lshlrev_b64 v[50:51], 11, v[50:51]
	v_lshl_add_u64 v[50:51], s[22:23], 0, v[50:51]
	v_mul_f32_e32 v46, v46, v251
	v_mul_f32_e32 v47, v47, v251
	v_mul_f32_e32 v48, v48, v251
	v_mul_f32_e32 v49, v49, v251
	v_cvt_pk_bf16_f32 v46, v46, v47
	v_cvt_pk_bf16_f32 v47, v48, v49
	v_mad_i64_i32 v[254:255], s[48:49], v132, s44, v[66:67]
	v_lshlrev_b64 v[254:255], 11, v[254:255]
	v_lshl_add_u64 v[254:255], s[22:23], 0, v[254:255]
	v_mul_f32_e32 v42, v42, v251
	v_mul_f32_e32 v43, v43, v251
	v_mul_f32_e32 v44, v44, v251
	v_mul_f32_e32 v45, v45, v251
	v_cvt_pk_bf16_f32 v48, v42, v43
	v_cvt_pk_bf16_f32 v49, v44, v45
	v_lshl_add_u64 v[44:45], v[134:135], 1, v[254:255]
	s_nop 1
	v_permlane16_swap_b32 v46, v48
	v_permlane16_swap_b32 v47, v49
	v_lshl_add_u64 v[254:255], v[44:45], 0, v[252:253]
	s_nop 0
	global_store_dwordx4 v[254:255], v[46:49], off offset:128
	s_nop 1
	v_mad_i64_i32 v[42:43], s[48:49], v132, s44, v[66:67]
	v_lshlrev_b64 v[42:43], 11, v[42:43]
	v_lshl_add_u64 v[42:43], s[22:23], 0, v[42:43]
	v_mul_f32_e32 v38, v38, v251
	v_mul_f32_e32 v39, v39, v251
	v_mul_f32_e32 v40, v40, v251
	v_mul_f32_e32 v41, v41, v251
	v_cvt_pk_bf16_f32 v38, v38, v39
	v_cvt_pk_bf16_f32 v39, v40, v41
	v_mad_i64_i32 v[254:255], s[48:49], v132, s44, v[66:67]
	v_lshlrev_b64 v[254:255], 11, v[254:255]
	v_lshl_add_u64 v[254:255], s[22:23], 0, v[254:255]
	v_mul_f32_e32 v34, v34, v251
	v_mul_f32_e32 v35, v35, v251
	v_mul_f32_e32 v36, v36, v251
	v_mul_f32_e32 v37, v37, v251
	v_cvt_pk_bf16_f32 v40, v34, v35
	v_cvt_pk_bf16_f32 v41, v36, v37
	v_lshl_add_u64 v[36:37], v[134:135], 1, v[254:255]
	s_nop 1
	v_permlane16_swap_b32 v38, v40
	v_permlane16_swap_b32 v39, v41
	v_lshl_add_u64 v[254:255], v[36:37], 0, v[252:253]
	s_nop 0
	global_store_dwordx4 v[254:255], v[38:41], off offset:192
	s_nop 1
	v_or_b32_e32 v34, 48, v136
	v_ashrrev_i32_e32 v35, 31, v34
	v_mad_i64_i32 v[36:37], s[10:11], v132, s44, v[136:137]
	v_lshl_add_u64 v[36:37], v[36:37], 2, s[26:27]
	v_add_co_u32_e32 v38, vcc, 0x12000, v36
	s_nop 1
	v_addc_co_u32_e32 v39, vcc, 0, v37, vcc
	s_nop 0
	v_add_f32_e32 v36, 0, v208
	v_add_f32_e32 v36, v36, v209
; __device__ __forceinline__ int get_tid512() { int t = threadIdx.x; asm volatile("" : "+v"(t)); return t; }
; __device__ __forceinline__ unsigned pack2(float a, float b) { unsigned r; asm("v_cvt_pk_bf16_f32 %0, %1, %2" : "=v"(r) : "v"(a), "v"(b)); return r; }
;   __device__ __forceinline__ void c4(int g, int rig, int col, f32x4 v) const {
;     const size_t row = (size_t)g * ostride + rig;
;     float s = 1.f;
;     if (NP > 0) {
;       float t = 0.f;
; #pragma unroll
;       for (int q = 0; q < NP; ++q) t += part[(size_t)q * pstride + row];
;       s = rsqrtf(t * inv_n + 1e-6f);
;     }
;     uint2 u; u.x = pack2(v[0] * s, v[1] * s); u.y = pack2(v[2] * s, v[3] * s);
;     *(uint2*)(out + row * ld + col) = u;
;   }
; template <bool SWAP, class Epi, bool THIN = false> ...
;     ...
;     const int te = get_tid512();
;     const int fr_e = te & 15, fq_e = (te & 63) >> 4, wr_e = te >> 7, wc_e = (te >> 6) & 1;
;     const int sub = 2 * mt + (wr_e >> 1);
;     const int g = sub / tpg, ti = sub - g * tpg;
;     const int rig0 = ti * step - halo;
;     const int rw = (wr_e & 1) * 64;
;     if constexpr (Epi::KIND == 0) {
; #pragma unroll
;       for (int m = 0; m < 4; ++m) {
;         const int rig = rig0 + rw + m * 16 + fr_e;
;         if constexpr (Epi::ROWSUM) {
;           float ss = 0.f;
; #pragma unroll
;           for (int n = 0; n < 8; ++n) {
;             const int col = nt * 256 + wc_e * 128 + n * 16 + fq_e * 4;
;             if (col < N) ss += epi.c4(g, rig, col, acc[m][n]);
;           }
;           ss += __shfl_xor(ss, 16); ss += __shfl_xor(ss, 32);
;           if (fq_e == 0) epi.rowsum(g, rig, nt * 2 + wc_e, ss);
;         } else {
; #pragma unroll
;           for (int n = 0; n < 8; ++n) {
;             const int col = nt * 256 + wc_e * 128 + n * 16 + fq_e * 4;
;             if (col < N) epi.c4(g, rig, col, acc[m][n]);
;           }
	v_fmamk_f32 v36, v36, 0x3b800000, v172
	v_mul_f32_e32 v37, 0x4b800000, v36
	v_cmp_gt_f32_e32 vcc, s47, v36
	s_nop 1
	v_cndmask_b32_e32 v36, v36, v37, vcc
	v_rsq_f32_e32 v38, v36
	v_mad_i64_i32 v[36:37], s[10:11], v132, s44, v[34:35]
	v_lshlrev_b64 v[36:37], 11, v[36:37]
	v_mul_f32_e32 v39, 0x45800000, v38
	v_cndmask_b32_e32 v38, v38, v39, vcc
	v_lshl_add_u64 v[36:37], s[22:23], 0, v[36:37]
	v_mov_b32_e32 v251, v38
	v_mul_f32_e32 v30, v30, v38
	v_mul_f32_e32 v31, v31, v38
	v_mul_f32_e32 v32, v32, v38
	v_mul_f32_e32 v33, v33, v38
	v_cvt_pk_bf16_f32 v30, v30, v31
	v_cvt_pk_bf16_f32 v31, v32, v33
	v_mad_i64_i32 v[254:255], s[12:13], v132, s44, v[34:35]
	v_lshlrev_b64 v[254:255], 11, v[254:255]
	v_lshl_add_u64 v[254:255], s[22:23], 0, v[254:255]
	v_mul_f32_e32 v26, v26, v251
	v_mul_f32_e32 v27, v27, v251
	v_mul_f32_e32 v28, v28, v251
	v_mul_f32_e32 v29, v29, v251
	v_cvt_pk_bf16_f32 v32, v26, v27
	v_cvt_pk_bf16_f32 v33, v28, v29
	v_lshl_add_u64 v[28:29], v[134:135], 1, v[254:255]
	s_nop 1
	v_permlane16_swap_b32 v30, v32
	v_permlane16_swap_b32 v31, v33
	v_lshl_add_u64 v[254:255], v[28:29], 0, v[252:253]
	s_nop 0
	global_store_dwordx4 v[254:255], v[30:33], off
	s_nop 1
	v_mad_i64_i32 v[26:27], s[12:13], v132, s44, v[34:35]
	v_lshlrev_b64 v[26:27], 11, v[26:27]
	v_lshl_add_u64 v[26:27], s[22:23], 0, v[26:27]
	v_mul_f32_e32 v22, v22, v251
	v_mul_f32_e32 v23, v23, v251
	v_mul_f32_e32 v24, v24, v251
	v_mul_f32_e32 v25, v25, v251
	v_cvt_pk_bf16_f32 v22, v22, v23
	v_cvt_pk_bf16_f32 v23, v24, v25
	v_mad_i64_i32 v[254:255], s[12:13], v132, s44, v[34:35]
	v_lshlrev_b64 v[254:255], 11, v[254:255]
	v_lshl_add_u64 v[254:255], s[22:23], 0, v[254:255]
	v_mul_f32_e32 v18, v18, v251
	v_mul_f32_e32 v19, v19, v251
	v_mul_f32_e32 v20, v20, v251
	v_mul_f32_e32 v21, v21, v251
	v_cvt_pk_bf16_f32 v24, v18, v19
	v_cvt_pk_bf16_f32 v25, v20, v21
	v_lshl_add_u64 v[20:21], v[134:135], 1, v[254:255]
	s_nop 1
	v_permlane16_swap_b32 v22, v24
	v_permlane16_swap_b32 v23, v25
	v_lshl_add_u64 v[254:255], v[20:21], 0, v[252:253]
	s_nop 0
	global_store_dwordx4 v[254:255], v[22:25], off offset:64
	s_nop 1
	v_mad_i64_i32 v[18:19], s[12:13], v132, s44, v[34:35]
	v_lshlrev_b64 v[18:19], 11, v[18:19]
	v_lshl_add_u64 v[18:19], s[22:23], 0, v[18:19]
	v_mul_f32_e32 v14, v14, v251
	v_mul_f32_e32 v15, v15, v251
	v_mul_f32_e32 v16, v16, v251
	v_mul_f32_e32 v17, v17, v251
	v_cvt_pk_bf16_f32 v14, v14, v15
	v_cvt_pk_bf16_f32 v15, v16, v17
	v_mad_i64_i32 v[254:255], s[8:9], v132, s44, v[34:35]
	v_lshlrev_b64 v[254:255], 11, v[254:255]
	v_lshl_add_u64 v[254:255], s[22:23], 0, v[254:255]
	v_mul_f32_e32 v10, v10, v251
	v_mul_f32_e32 v11, v11, v251
	v_mul_f32_e32 v12, v12, v251
	v_mul_f32_e32 v13, v13, v251
	v_cvt_pk_bf16_f32 v16, v10, v11
	v_cvt_pk_bf16_f32 v17, v12, v13
	v_lshl_add_u64 v[12:13], v[134:135], 1, v[254:255]
	s_nop 1
	v_permlane16_swap_b32 v14, v16
	v_permlane16_swap_b32 v15, v17
	v_lshl_add_u64 v[254:255], v[12:13], 0, v[252:253]
	s_nop 0
	global_store_dwordx4 v[254:255], v[14:17], off offset:128
	s_nop 1
	v_mad_i64_i32 v[10:11], s[6:7], v132, s44, v[34:35]
	v_lshlrev_b64 v[10:11], 11, v[10:11]
	v_lshl_add_u64 v[10:11], s[22:23], 0, v[10:11]
	v_mul_f32_e32 v6, v6, v251
	v_mul_f32_e32 v7, v7, v251
	v_mul_f32_e32 v8, v8, v251
	v_mul_f32_e32 v9, v9, v251
	v_cvt_pk_bf16_f32 v6, v6, v7
	v_cvt_pk_bf16_f32 v7, v8, v9
	v_mad_i64_i32 v[254:255], s[4:5], v132, s44, v[34:35]
	v_lshlrev_b64 v[254:255], 11, v[254:255]
	v_lshl_add_u64 v[254:255], s[22:23], 0, v[254:255]
	v_mul_f32_e32 v2, v2, v251
	v_mul_f32_e32 v3, v3, v251
	v_mul_f32_e32 v4, v4, v251
	v_mul_f32_e32 v5, v5, v251
	v_cvt_pk_bf16_f32 v8, v2, v3
	v_cvt_pk_bf16_f32 v9, v4, v5
	v_lshl_add_u64 v[4:5], v[134:135], 1, v[254:255]
	s_nop 1
	v_permlane16_swap_b32 v6, v8
	v_permlane16_swap_b32 v7, v9
	v_lshl_add_u64 v[254:255], v[4:5], 0, v[252:253]
	s_nop 0
	global_store_dwordx4 v[254:255], v[6:9], off offset:192
	s_nop 1
	s_branch .LBB0_1817
